# dynamic conversion claims fetched one block ahead (the atomic for the next block is in flight while the current block is converted)
# speedup vs baseline: 1.0128x; 1.0028x over previous
.Lmy_sb_mid:
	s_or_b64 exec, exec, s[4:5]
	s_cmp_gt_u32 s40, 5
	s_cbranch_scc1 .Lmy_cvm_skip
	v_mov_b32_e32 v37, v237
	v_readlane_b32 s6, v254, 0
	v_readfirstlane_b32 s5, v37
	s_ashr_i32 s5, s5, 6
	s_add_i32 s12, s5, s6
	s_mov_b32 s101, s12
	v_readfirstlane_b32 s100, v237
	s_cmp_gt_u32 s100, 63
	s_cbranch_scc1 .Lmy_cv5_w
	s_mov_b64 s[44:45], exec
	s_mov_b64 exec, 1
	s_lshl_b32 s100, s40, 8
	s_add_i32 s100, s100, 0x5000
	v_mov_b32_e32 v90, s100
	v_mov_b32_e32 v91, 1
	global_atomic_add v91, v90, v91, s[36:37] sc0
	s_waitcnt vmcnt(0)
	v_readfirstlane_b32 s32, v91
	v_mov_b32_e32 v93, 0x21008
	v_mov_b32_e32 v92, s32
	ds_write_b32 v93, v92
	s_lshl_b32 s100, s40, 8
	s_add_i32 s100, s100, 0x5000
	v_mov_b32_e32 v90, s100
	v_mov_b32_e32 v91, 1
	global_atomic_add v91, v90, v91, s[36:37] sc0
	s_waitcnt lgkmcnt(0)
	s_mov_b64 exec, s[44:45]
.Lmy_cv5_w:
	s_barrier
	v_mov_b32_e32 v93, 0x21008
	ds_read_b32 v93, v93
	s_waitcnt lgkmcnt(0)
	s_barrier
	v_readfirstlane_b32 s12, v93
	v_readfirstlane_b32 s100, v237
	s_lshr_b32 s100, s100, 6
	s_lshl_b32 s12, s12, 3
	s_add_i32 s12, s12, s100
	s_load_dwordx2 s[6:7], s[0:1], 0x80
	s_add_i32 s4, s56, 1
	s_lshl_b32 s5, s5, 14
	s_add_i32 s13, s5, 0
	s_lshr_b32 s42, s4, 1
	s_lshl_b32 s4, s4, 12
	s_waitcnt lgkmcnt(0)
	s_add_u32 s6, s6, s4
	v_and_b32_e32 v36, 63, v37
	s_addc_u32 s7, s7, 0
	s_andn2_b64 vcc, exec, s[58:59]
	s_mov_b64 s[4:5], -1
	s_cbranch_vccnz .LBB0_301
	s_load_dwordx2 s[8:9], s[0:1], 0x8
	s_mul_i32 s5, s42, 0x600000
	s_mul_hi_u32 s4, s42, 0x600000
	s_waitcnt lgkmcnt(0)
	s_add_u32 s14, s8, s5
	s_addc_u32 s15, s9, s4
	s_load_dwordx2 s[8:9], s[0:1], 0x20
	s_lshl_b64 s[4:5], s[42:43], 22
	s_waitcnt lgkmcnt(0)
	s_add_u32 s16, s8, s4
	s_addc_u32 s17, s9, s5
	s_cmpk_lt_i32 s12, 0x500
	s_cselect_b64 s[8:9], -1, 0
	s_cmpk_gt_i32 s12, 0x4ff
	s_cbranch_scc1 .LBB0_231
	s_cmpk_gt_i32 s12, 0x2ff
	s_cselect_b64 s[4:5], -1, 0
	s_and_b64 s[10:11], s[4:5], exec
	s_movk_i32 s10, 0x600
	s_cselect_b32 s18, 0x400, s10
	s_cselect_b32 s20, 0xfffffd00, 0
	s_lshr_b32 s19, s18, 5
	s_abs_i32 s10, s19
	v_cvt_f32_u32_e32 v0, s10
	s_sub_i32 s22, 0, s10
	s_add_i32 s20, s20, s12
	s_abs_i32 s21, s20
	v_rcp_iflag_f32_e32 v0, v0
	s_xor_b32 s11, s20, s19
	s_ashr_i32 s11, s11, 31
	v_lshrrev_b32_e32 v2, 5, v36
	v_mul_f32_e32 v0, 0x4f7ffffe, v0
	v_cvt_u32_f32_e32 v0, v0
	v_mov_b32_e32 v8, 1.0
	v_readfirstlane_b32 s23, v0
	s_mul_i32 s22, s22, s23
	s_mul_hi_u32 s22, s23, s22
	s_add_i32 s23, s23, s22
	s_mul_hi_u32 s22, s21, s23
	s_mul_i32 s23, s22, s10
	s_sub_i32 s21, s21, s23
	s_add_i32 s24, s22, 1
	s_sub_i32 s23, s21, s10
	s_cmp_ge_u32 s21, s10
	s_cselect_b32 s22, s24, s22
	s_cselect_b32 s21, s23, s21
	s_add_i32 s23, s22, 1
	s_cmp_ge_u32 s21, s10
	s_cselect_b32 s10, s23, s22
	s_xor_b32 s10, s10, s11
	s_sub_i32 s21, s10, s11
	v_lshl_or_b32 v2, s21, 6, v2
	s_or_b64 s[10:11], s[4:5], s[92:93]
	v_ashrrev_i32_e32 v3, 31, v2
	s_and_b64 vcc, exec, s[10:11]
	v_lshl_add_u64 v[6:7], v[2:3], 2, s[6:7]
	v_mov_b32_e32 v3, 1.0
	s_cbranch_vccnz .LBB0_168
	global_load_dword v3, v[6:7], off

.LBB0_235:
	v_add_u32_e32 v35, 0x400, v44
	ds_write2_b32 v44, v2, v3 offset1:66
	ds_write2_b32 v44, v4, v5 offset0:132 offset1:198
	ds_write2_b32 v35, v6, v7 offset0:8 offset1:74
	ds_write2_b32 v35, v8, v9 offset0:140 offset1:206
	v_add_u32_e32 v35, 0x800, v44
	ds_write2_b32 v35, v10, v11 offset0:16 offset1:82
	ds_write2_b32 v35, v12, v13 offset0:148 offset1:214
	v_add_u32_e32 v35, 0xc00, v44
	v_readfirstlane_b32 s100, v237
	s_cmp_gt_u32 s100, 63
	s_cbranch_scc1 .Lmy_cv4_w
	s_mov_b64 s[44:45], exec
	s_mov_b64 exec, 1
	s_waitcnt vmcnt(0)
	v_readfirstlane_b32 s32, v91
	v_mov_b32_e32 v93, 0x21008
	v_mov_b32_e32 v92, s32
	ds_write_b32 v93, v92
	s_lshl_b32 s100, s40, 8
	s_add_i32 s100, s100, 0x5000
	v_mov_b32_e32 v90, s100
	v_mov_b32_e32 v91, 1
	global_atomic_add v91, v90, v91, s[36:37] sc0
	s_waitcnt lgkmcnt(0)
	s_mov_b64 exec, s[44:45]
.Lmy_cv4_w:
	s_barrier
	v_mov_b32_e32 v93, 0x21008
	ds_read_b32 v93, v93
	s_waitcnt lgkmcnt(0)
	s_barrier
	v_readfirstlane_b32 s18, v93
	v_readfirstlane_b32 s100, v237
	s_lshr_b32 s100, s100, 6
	s_lshl_b32 s18, s18, 3
	s_add_i32 s18, s18, s100
	ds_write2_b32 v35, v14, v15 offset0:24 offset1:90
	ds_write2_b32 v35, v16, v17 offset0:156 offset1:222
	v_add_u32_e32 v35, 0x1000, v44
	ds_write2_b32 v35, v18, v19 offset0:32 offset1:98
	ds_write2_b32 v35, v20, v21 offset0:164 offset1:230
	v_add_u32_e32 v35, 0x1400, v44
	s_cmpk_gt_i32 s18, 0x4ff
	ds_write2_b32 v35, v22, v23 offset0:40 offset1:106
	ds_write2_b32 v35, v24, v25 offset0:172 offset1:238
	v_add_u32_e32 v35, 0x1800, v44
	s_cselect_b64 s[8:9], -1, 0
	ds_write2_b32 v35, v26, v27 offset0:48 offset1:114
	ds_write2_b32 v35, v28, v29 offset0:180 offset1:246
	v_add_u32_e32 v35, 0x1c00, v44
	s_and_b64 vcc, exec, s[8:9]
	ds_write2_b32 v35, v30, v31 offset0:56 offset1:122
	ds_write2_b32 v35, v32, v33 offset0:188 offset1:254
	s_cbranch_vccnz .LBB0_234
	s_cmpk_gt_i32 s18, 0x2ff
	s_cselect_b64 s[4:5], -1, 0
	s_and_b64 s[10:11], s[4:5], exec
	s_movk_i32 s10, 0x600
	s_cselect_b32 s20, 0x400, s10
	s_cselect_b32 s10, 0xfffffd00, 0
	s_lshr_b32 s21, s20, 5
	s_abs_i32 s11, s21
	v_cvt_f32_u32_e32 v2, s11
	s_sub_i32 s24, 0, s11
	s_add_i32 s22, s18, s10
	v_rcp_iflag_f32_e32 v2, v2
	s_abs_i32 s23, s22
	s_xor_b32 s10, s22, s21
	s_ashr_i32 s10, s10, 31
	v_mul_f32_e32 v2, 0x4f7ffffe, v2
	v_cvt_u32_f32_e32 v2, v2
	v_mov_b32_e32 v8, 1.0
	v_readfirstlane_b32 s25, v2
	s_mul_i32 s24, s24, s25
	s_mul_hi_u32 s24, s25, s24
	s_add_i32 s25, s25, s24
	s_mul_hi_u32 s24, s23, s25
	s_mul_i32 s25, s24, s11
	s_sub_i32 s23, s23, s25
	s_add_i32 s26, s24, 1
	s_sub_i32 s25, s23, s11
	s_cmp_ge_u32 s23, s11
	s_cselect_b32 s24, s26, s24
	s_cselect_b32 s23, s25, s23
	s_add_i32 s25, s24, 1
	s_cmp_ge_u32 s23, s11
	s_cselect_b32 s11, s25, s24
	s_xor_b32 s11, s11, s10
	s_sub_i32 s23, s11, s10
	v_lshl_or_b32 v2, s23, 6, v38
	s_or_b64 s[10:11], s[4:5], s[92:93]
	v_ashrrev_i32_e32 v3, 31, v2
	s_and_b64 vcc, exec, s[10:11]
	v_lshl_add_u64 v[6:7], v[2:3], 2, s[6:7]
	v_mov_b32_e32 v3, 1.0
	s_cbranch_vccnz .LBB0_238
	global_load_dword v3, v[6:7], off

.LBB0_372:
	v_add_u32_e32 v35, 0x400, v43
	ds_write2_b32 v43, v2, v3 offset1:66
	ds_write2_b32 v43, v4, v5 offset0:132 offset1:198
	ds_write2_b32 v35, v6, v7 offset0:8 offset1:74
	ds_write2_b32 v35, v8, v9 offset0:140 offset1:206
	v_add_u32_e32 v35, 0x800, v43
	ds_write2_b32 v35, v10, v11 offset0:16 offset1:82
	ds_write2_b32 v35, v12, v13 offset0:148 offset1:214
	v_add_u32_e32 v35, 0xc00, v43
	v_readfirstlane_b32 s100, v237
	s_cmp_gt_u32 s100, 63
	s_cbranch_scc1 .Lmy_cv3_w
	s_mov_b64 s[44:45], exec
	s_mov_b64 exec, 1
	s_waitcnt vmcnt(0)
	v_readfirstlane_b32 s32, v91
	v_mov_b32_e32 v93, 0x21008
	v_mov_b32_e32 v92, s32
	ds_write_b32 v93, v92
	s_lshl_b32 s100, s40, 8
	s_add_i32 s100, s100, 0x5000
	v_mov_b32_e32 v90, s100
	v_mov_b32_e32 v91, 1
	global_atomic_add v91, v90, v91, s[36:37] sc0
	s_waitcnt lgkmcnt(0)
	s_mov_b64 exec, s[44:45]
.Lmy_cv3_w:
	s_barrier
	v_mov_b32_e32 v93, 0x21008
	ds_read_b32 v93, v93
	s_waitcnt lgkmcnt(0)
	s_barrier
	v_readfirstlane_b32 s13, v93
	v_readfirstlane_b32 s100, v237
	s_lshr_b32 s100, s100, 6
	s_lshl_b32 s13, s13, 3
	s_add_i32 s13, s13, s100
	ds_write2_b32 v35, v14, v15 offset0:24 offset1:90
	ds_write2_b32 v35, v16, v17 offset0:156 offset1:222
	v_add_u32_e32 v35, 0x1000, v43
	ds_write2_b32 v35, v18, v19 offset0:32 offset1:98
	ds_write2_b32 v35, v20, v21 offset0:164 offset1:230
	v_add_u32_e32 v35, 0x1400, v43
	s_cmpk_gt_i32 s13, 0x11ff
	ds_write2_b32 v35, v22, v23 offset0:40 offset1:106
	ds_write2_b32 v35, v24, v25 offset0:172 offset1:238
	v_add_u32_e32 v35, 0x1800, v43
	s_cselect_b64 s[8:9], -1, 0
	ds_write2_b32 v35, v26, v27 offset0:48 offset1:114
	ds_write2_b32 v35, v28, v29 offset0:180 offset1:246
	v_add_u32_e32 v35, 0x1c00, v43
	s_and_b64 vcc, exec, s[8:9]
	ds_write2_b32 v35, v30, v31 offset0:56 offset1:122
	ds_write2_b32 v35, v32, v33 offset0:188 offset1:254
	s_cbranch_vccnz .LBB0_371
	s_cmpk_gt_i32 s13, 0xbff
	s_cselect_b64 s[4:5], -1, 0
	s_and_b64 s[10:11], s[4:5], exec
	s_cselect_b32 s19, 0x400, s85
	s_cselect_b32 s10, 0xfffff400, 0
	s_lshr_b32 s20, s19, 5
	s_abs_i32 s11, s20
	v_cvt_f32_u32_e32 v2, s11
	s_sub_i32 s23, 0, s11
	s_add_i32 s21, s13, s10
	v_rcp_iflag_f32_e32 v2, v2
	s_abs_i32 s22, s21
	s_xor_b32 s10, s21, s20
	s_ashr_i32 s10, s10, 31
	v_mul_f32_e32 v2, 0x4f7ffffe, v2
	v_cvt_u32_f32_e32 v2, v2
	v_mov_b32_e32 v8, 1.0
	v_readfirstlane_b32 s24, v2
	s_mul_i32 s23, s23, s24
	s_mul_hi_u32 s23, s24, s23
	s_add_i32 s24, s24, s23
	s_mul_hi_u32 s23, s22, s24
	s_mul_i32 s24, s23, s11
	s_sub_i32 s22, s22, s24
	s_add_i32 s25, s23, 1
	s_sub_i32 s24, s22, s11
	s_cmp_ge_u32 s22, s11
	s_cselect_b32 s23, s25, s23
	s_cselect_b32 s22, s24, s22
	s_add_i32 s24, s23, 1
	s_cmp_ge_u32 s22, s11
	s_cselect_b32 s11, s24, s23
	s_xor_b32 s11, s11, s10
	s_sub_i32 s22, s11, s10
	v_lshl_or_b32 v2, s22, 6, v38
	s_or_b64 s[10:11], s[4:5], s[92:93]
	v_ashrrev_i32_e32 v3, 31, v2
	s_and_b64 vcc, exec, s[10:11]
	v_lshl_add_u64 v[6:7], v[2:3], 2, s[6:7]
	v_mov_b32_e32 v3, 1.0
	s_cbranch_vccnz .LBB0_375
	global_load_dword v3, v[6:7], off

.Lmy_sa_mid:
	s_or_b64 exec, exec, s[4:5]
	v_mov_b32_e32 v35, v237
	s_mul_i32 s7, s56, 0x1600000
	v_readfirstlane_b32 s4, v35
	s_ashr_i32 s19, s4, 6
	v_readlane_b32 s4, v254, 0
	v_readfirstlane_b32 s100, v237
	s_cmp_gt_u32 s100, 63
	s_cbranch_scc1 .Lmy_cv2_w
	s_mov_b64 s[44:45], exec
	s_mov_b64 exec, 1
	s_lshl_b32 s100, s40, 8
	s_add_i32 s100, s100, 0x5000
	v_mov_b32_e32 v90, s100
	v_mov_b32_e32 v91, 1
	global_atomic_add v91, v90, v91, s[36:37] sc0
	s_waitcnt vmcnt(0)
	v_readfirstlane_b32 s32, v91
	v_mov_b32_e32 v93, 0x21008
	v_mov_b32_e32 v92, s32
	ds_write_b32 v93, v92
	s_lshl_b32 s100, s40, 8
	s_add_i32 s100, s100, 0x5000
	v_mov_b32_e32 v90, s100
	v_mov_b32_e32 v91, 1
	global_atomic_add v91, v90, v91, s[36:37] sc0
	s_waitcnt lgkmcnt(0)
	s_mov_b64 exec, s[44:45]
.Lmy_cv2_w:
	s_barrier
	v_mov_b32_e32 v93, 0x21008
	ds_read_b32 v93, v93
	s_waitcnt lgkmcnt(0)
	s_barrier
	v_readfirstlane_b32 s18, v93
	v_readfirstlane_b32 s100, v237
	s_lshr_b32 s100, s100, 6
	s_lshl_b32 s18, s18, 3
	s_add_i32 s18, s18, s100
	s_load_dwordx2 s[4:5], s[0:1], 0x60
	s_load_dwordx2 s[10:11], s[0:1], 0x78
	s_load_dwordx2 s[8:9], s[0:1], 0x90
	s_mov_b32 s57, s43
	s_mul_hi_u32 s6, s56, 0x1600000
	v_and_b32_e32 v34, 63, v35
	s_waitcnt lgkmcnt(0)
	s_add_u32 s14, s4, s7
	s_addc_u32 s15, s5, s6
	s_lshl_b64 s[4:5], s[56:57], 12
	s_add_u32 s6, s8, s4
	s_addc_u32 s7, s9, s5
	s_mul_i32 s5, s56, 0xb00000
	s_mul_hi_u32 s4, s56, 0xb00000
	s_add_u32 s16, s10, s5
	s_addc_u32 s17, s11, s4
	s_cmpk_lt_i32 s18, 0x1080
	s_cselect_b64 s[10:11], -1, 0
	s_cmpk_gt_i32 s18, 0x107f
	v_lshrrev_b32_e32 v36, 5, v34
	s_cbranch_scc1 .LBB0_609
	s_cmpk_gt_i32 s18, 0xaff
	s_cselect_b64 s[4:5], -1, 0
	s_and_b64 s[12:13], s[4:5], exec
	s_cselect_b32 s20, 0x400, s3
	s_cselect_b32 s22, 0xfffff500, 0
	s_lshr_b32 s21, s20, 5
	s_abs_i32 s12, s21
	v_cvt_f32_u32_e32 v0, s12
	s_sub_i32 s24, 0, s12
	s_add_i32 s22, s22, s18
	s_abs_i32 s23, s22
	v_rcp_iflag_f32_e32 v0, v0
	s_xor_b32 s13, s22, s21
	s_ashr_i32 s13, s13, 31
	v_mov_b32_e32 v8, 1.0
	v_mul_f32_e32 v0, 0x4f7ffffe, v0
	v_cvt_u32_f32_e32 v0, v0
	s_nop 0
	v_readfirstlane_b32 s25, v0
	s_mul_i32 s24, s24, s25
	s_mul_hi_u32 s24, s25, s24
	s_add_i32 s25, s25, s24
	s_mul_hi_u32 s24, s23, s25
	s_mul_i32 s25, s24, s12
	s_sub_i32 s23, s23, s25
	s_add_i32 s26, s24, 1
	s_sub_i32 s25, s23, s12
	s_cmp_ge_u32 s23, s12
	s_cselect_b32 s24, s26, s24
	s_cselect_b32 s23, s25, s23
	s_add_i32 s25, s24, 1
	s_cmp_ge_u32 s23, s12
	s_cselect_b32 s12, s25, s24
	s_xor_b32 s12, s12, s13
	s_sub_i32 s23, s12, s13
	s_cmp_eq_u64 s[8:9], 0
	v_lshl_or_b32 v2, s23, 6, v36
	s_cselect_b64 s[12:13], -1, 0
	s_or_b64 s[12:13], s[4:5], s[12:13]
	v_ashrrev_i32_e32 v3, 31, v2
	s_and_b64 vcc, exec, s[12:13]
	v_lshl_add_u64 v[6:7], v[2:3], 2, s[6:7]
	v_mov_b32_e32 v3, 1.0
	s_cbranch_vccnz .LBB0_546
	global_load_dword v3, v[6:7], off

.LBB0_612:
	v_add_u32_e32 v35, 0x400, v42
	ds_write2_b32 v42, v2, v3 offset1:66
	ds_write2_b32 v42, v4, v5 offset0:132 offset1:198
	ds_write2_b32 v35, v6, v7 offset0:8 offset1:74
	ds_write2_b32 v35, v8, v9 offset0:140 offset1:206
	v_add_u32_e32 v35, 0x800, v42
	ds_write2_b32 v35, v10, v11 offset0:16 offset1:82
	ds_write2_b32 v35, v12, v13 offset0:148 offset1:214
	v_add_u32_e32 v35, 0xc00, v42
	v_readfirstlane_b32 s100, v237
	s_cmp_gt_u32 s100, 63
	s_cbranch_scc1 .Lmy_cv1_w
	s_mov_b64 s[44:45], exec
	s_mov_b64 exec, 1
	s_waitcnt vmcnt(0)
	v_readfirstlane_b32 s32, v91
	v_mov_b32_e32 v93, 0x21008
	v_mov_b32_e32 v92, s32
	ds_write_b32 v93, v92
	s_lshl_b32 s100, s40, 8
	s_add_i32 s100, s100, 0x5000
	v_mov_b32_e32 v90, s100
	v_mov_b32_e32 v91, 1
	global_atomic_add v91, v90, v91, s[36:37] sc0
	s_waitcnt lgkmcnt(0)
	s_mov_b64 exec, s[44:45]
.Lmy_cv1_w:
	s_barrier
	v_mov_b32_e32 v93, 0x21008
	ds_read_b32 v93, v93
	s_waitcnt lgkmcnt(0)
	s_barrier
	v_readfirstlane_b32 s19, v93
	v_readfirstlane_b32 s100, v237
	s_lshr_b32 s100, s100, 6
	s_lshl_b32 s19, s19, 3
	s_add_i32 s19, s19, s100
	ds_write2_b32 v35, v14, v15 offset0:24 offset1:90
	ds_write2_b32 v35, v16, v17 offset0:156 offset1:222
	v_add_u32_e32 v35, 0x1000, v42
	ds_write2_b32 v35, v18, v19 offset0:32 offset1:98
	ds_write2_b32 v35, v20, v21 offset0:164 offset1:230
	v_add_u32_e32 v35, 0x1400, v42
	s_cmpk_gt_i32 s19, 0x107f
	ds_write2_b32 v35, v22, v23 offset0:40 offset1:106
	ds_write2_b32 v35, v24, v25 offset0:172 offset1:238
	v_add_u32_e32 v35, 0x1800, v42
	s_cselect_b64 s[10:11], -1, 0
	ds_write2_b32 v35, v26, v27 offset0:48 offset1:114
	ds_write2_b32 v35, v28, v29 offset0:180 offset1:246
	v_add_u32_e32 v35, 0x1c00, v42
	s_and_b64 vcc, exec, s[10:11]
	ds_write2_b32 v35, v30, v31 offset0:56 offset1:122
	ds_write2_b32 v35, v32, v33 offset0:188 offset1:254
	s_cbranch_vccnz .LBB0_678
	s_cmpk_gt_i32 s19, 0xaff
	s_cselect_b64 s[4:5], -1, 0
	s_and_b64 s[12:13], s[4:5], exec
	s_cselect_b32 s20, 0x400, s3
	s_cselect_b32 s12, 0xfffff500, 0
	s_lshr_b32 s21, s20, 5
	s_abs_i32 s13, s21
	v_cvt_f32_u32_e32 v2, s13
	s_sub_i32 s24, 0, s13
	s_add_i32 s22, s19, s12
	v_rcp_iflag_f32_e32 v2, v2
	s_abs_i32 s23, s22
	s_xor_b32 s12, s22, s21
	s_ashr_i32 s12, s12, 31
	v_mul_f32_e32 v2, 0x4f7ffffe, v2
	v_cvt_u32_f32_e32 v2, v2
	v_mov_b32_e32 v8, 1.0
	v_readfirstlane_b32 s25, v2
	s_mul_i32 s24, s24, s25
	s_mul_hi_u32 s24, s25, s24
	s_add_i32 s25, s25, s24
	s_mul_hi_u32 s24, s23, s25
	s_mul_i32 s25, s24, s13
	s_sub_i32 s23, s23, s25
	s_add_i32 s26, s24, 1
	s_sub_i32 s25, s23, s13
	s_cmp_ge_u32 s23, s13
	s_cselect_b32 s24, s26, s24
	s_cselect_b32 s23, s25, s23
	s_add_i32 s25, s24, 1
	s_cmp_ge_u32 s23, s13
	s_cselect_b32 s13, s25, s24
	s_xor_b32 s13, s13, s12
	s_sub_i32 s23, s13, s12
	v_lshl_or_b32 v2, s23, 6, v36
	s_or_b64 s[12:13], s[4:5], s[8:9]
	v_ashrrev_i32_e32 v3, 31, v2
	s_and_b64 vcc, exec, s[12:13]
	v_lshl_add_u64 v[6:7], v[2:3], 2, s[6:7]
	v_mov_b32_e32 v3, 1.0
	s_cbranch_vccnz .LBB0_615
	global_load_dword v3, v[6:7], off
